# row phases: one L2 touch load per iteration for the next iteration's row pair (youngest op, data wait becomes vmcnt(1)) so each wave keeps two row pairs in flight
# baseline (speedup 1.0000x reference)
; __device__ __forceinline__ void phase_rows(const Params& p, const RowArgs& a, int G, int wave, int lane) {
;     bf16_t* XN = (bf16_t*)(p.ws + WS_XN);
;     const int gw = blockIdx.x * NWAVES + wave, NGW = G * NWAVES;
;     f32x4 gpo[4], gpr[4];
; #pragma unroll
;     for (int j = 0; j < 4; ++j) { const int c = 8 * lane + 512 * (j >> 1) + 4 * (j & 1);
;         gpo[j] = a.has_y ? *(const f32x4*)(a.gpost + c) : (f32x4){0.f, 0.f, 0.f, 0.f};
;         gpr[j] = a.write_xn ? *(const f32x4*)(a.gpre + c) : (f32x4){0.f, 0.f, 0.f, 0.f}; }
;     const int wpb = NGW / NB;
;     const bool bmaj = (NGW % NB == 0) && ((SEQ / 2) % wpb == 0);
;     const int ppw = bmaj ? (SEQ / 2) / wpb : 0;
;     const int nit = bmaj ? ppw + ((a.nrows > ML) ? ((a.nrows - ML) / 2 + NGW - 1) / NGW : 0) : (a.nrows / 2 + NGW - 1) / NGW;
;     int cur_rb = -1;
;     f32x4 gt[4], sh[4], sc[4];
; #pragma unroll 1
;     for (int it = (a.ctx_only && bmaj) ? ppw : 0; it < nit; ++it) {
;         int mp;
;         if (bmaj) mp = (it < ppw) ? (gw / wpb) * (SEQ / 2) + (gw % wpb) + it * wpb : ML / 2 + gw + (it - ppw) * NGW;
;         else mp = ((a.ctx_only && !bmaj) ? ML / 2 : 0) + gw + it * NGW;
.LBB0_201:
	v_readlane_b32 s0, v255, 17
	v_readlane_b32 s1, v255, 18
	s_mov_b32 s4, s0
	s_mul_i32 s1, s4, 0x36000
	s_mul_hi_i32 s0, s0, 0x36000
	s_add_u32 s16, s73, s1
	s_addc_u32 s17, s57, s0
	v_readlane_b32 s0, v254, 22
	s_add_i32 s18, s87, s0
	s_abs_i32 s1, s18
	v_readlane_b32 s4, v254, 8
	s_mul_hi_u32 s4, s1, s4
	v_readlane_b32 s7, v254, 9
	s_mul_i32 s5, s4, s7
	s_ashr_i32 s0, s18, 31
	s_sub_i32 s1, s1, s5
	s_lshl_b32 s19, s97, 7
	s_xor_b32 s0, s0, s59
	s_add_i32 s5, s4, 1
	s_sub_i32 s6, s1, s7
	s_cmp_ge_u32 s1, s7
	s_cselect_b32 s4, s5, s4
	s_cselect_b32 s1, s6, s1
	s_add_i32 s5, s4, 1
	s_cmp_ge_u32 s1, s7
	s_cselect_b32 s1, s5, s4
	s_xor_b32 s1, s1, s0
	s_sub_i32 s0, s1, s0
	s_lshl_b32 s1, s0, 11
	s_mul_i32 s0, s0, s3
	s_sub_i32 s20, s18, s0
	v_readlane_b32 s0, v254, 26
	v_or_b32_e32 v34, 0x200, v32
	v_lshlrev_b32_e32 v170, 1, v32
	v_mov_b32_e32 v171, v157
	v_lshlrev_b32_e32 v156, 2, v32
	s_add_i32 s20, s20, s1
	s_add_i32 s0, s0, s87
	s_mul_i32 s1, s52, s12
	v_mov_b32_e32 v48, 0
	v_lshl_add_u64 v[172:173], s[98:99], 0, v[170:171]
	v_lshl_add_u64 v[174:175], s[94:95], 0, v[170:171]
	v_lshl_add_u64 v[176:177], s[42:43], 0, v[156:157]
	s_sub_i32 s21, s0, s1
	s_mov_b32 s22, 0
	s_mov_b32 s10, -1
	v_lshlrev_b32_e32 v167, 2, v34
	v_and_b32_e32 v250, 0x1f0, v170
	v_lshlrev_b32_e32 v250, 3, v250
	s_lshl_b32 s32, s52, 12
	v_add_u32_e32 v250, s32, v250
	v_mov_b32_e32 v251, 0
	v_mov_b32_e32 v49, v48
	v_mov_b32_e32 v50, v48
	v_mov_b32_e32 v51, v48
	v_mov_b32_e32 v52, v48
	v_mov_b32_e32 v53, v48
	v_mov_b32_e32 v54, v48
	v_mov_b32_e32 v55, v48
	v_mov_b32_e32 v68, v48
	v_mov_b32_e32 v69, v48
	v_mov_b32_e32 v70, v48
	v_mov_b32_e32 v71, v48
	v_mov_b32_e32 v64, v48
	v_mov_b32_e32 v65, v48
	v_mov_b32_e32 v66, v48
	v_mov_b32_e32 v67, v48
	v_mov_b32_e32 v60, v48
	v_mov_b32_e32 v61, v48
	v_mov_b32_e32 v62, v48
	v_mov_b32_e32 v63, v48
	v_mov_b32_e32 v56, v48
	v_mov_b32_e32 v57, v48
	v_mov_b32_e32 v58, v48
	v_mov_b32_e32 v59, v48
	v_mov_b32_e32 v76, v48
	v_mov_b32_e32 v77, v48
	v_mov_b32_e32 v78, v48
	v_mov_b32_e32 v79, v48
	v_mov_b32_e32 v72, v48
	v_mov_b32_e32 v73, v48
	v_mov_b32_e32 v74, v48
	v_mov_b32_e32 v75, v48
	s_branch .LBB0_205

; __device__ __forceinline__ f32x4 bfx4_lo(u32x4 w) { return (f32x4){bf_lo(w.x), bf_hi(w.x), bf_lo(w.y), bf_hi(w.y)}; }
; __device__ __forceinline__ void phase_rows(const Params& p, const RowArgs& a, int G, int wave, int lane) {
;     ...
;         if (bmaj) mp = (it < ppw) ? (gw / wpb) * (SEQ / 2) + (gw % wpb) + it * wpb : ML / 2 + gw + (it - ppw) * NGW;
;         else mp = ((a.ctx_only && !bmaj) ? ML / 2 : 0) + gw + it * NGW;
;         if (mp >= a.nrows / 2) break;
;         const int m0 = 2 * mp; const bool isl = m0 < ML; const int rb = isl ? (m0 >> 12) : 8;
;         const bool use_y = a.has_y && !(a.lat_no_y && isl);
;         const size_t xoff = isl ? (size_t)m0 * DM : (size_t)(m0 - ML) * DM;
;         const void* xrb = isl ? a.xlat : a.xctx; void* xob = isl ? a.olat : a.octx;
;         bf16_t* xn = XN + (size_t)m0 * DM;
;         const size_t moff = (size_t)rb * NMOD;
;         f32x4 v[2][4], y[2][4];
;         if (a.xin_f32) {
; #pragma unroll
;             for (int u = 0; u < 2; ++u)
; #pragma unroll
;                 for (int j = 0; j < 4; ++j) v[u][j] = *(const f32x4*)((const float*)xrb + xoff + u * DM + 8 * lane + 512 * (j >> 1) + 4 * (j & 1));
;         } else {
; #pragma unroll
;             for (int u = 0; u < 2; ++u)
; #pragma unroll
;                 for (int jb = 0; jb < 2; ++jb) { const u32x4 xw = *(const u32x4*)((const bf16_t*)xrb + xoff + u * DM + 8 * lane + 512 * jb); v[u][2 * jb] = bfx4_lo(xw); v[u][2 * jb + 1] = bfx4_hi(xw); }
;         }
;         if (use_y) {
;             if (isl || !a.ctx_split) {
; #pragma unroll
;                 for (int u = 0; u < 2; ++u)
; #pragma unroll
;                     for (int jb = 0; jb < 2; ++jb) { const u32x4 yw = *(const u32x4*)(xn + u * DM + 8 * lane + 512 * jb); y[u][2 * jb] = bfx4_lo(yw); y[u][2 * jb + 1] = bfx4_hi(yw); }
;             } else {
;                 const float* part = (const float*)p.out;
; #pragma unroll
;                 for (int u = 0; u < 2; ++u)
; #pragma unroll
;                     for (int j = 0; j < 4; ++j) { const float* pp = part + (size_t)(m0 + u - ML) * DM + 8 * lane + 512 * (j >> 1) + 4 * (j & 1); f32x4 s = *(const f32x4*)pp;
; #pragma unroll
;                         for (int k = 1; k < pg8::KSPLIT; ++k) s += *(const f32x4*)(pp + (size_t)k * MC * DM);
;                         y[u][j] = s; }
.LBB0_210:
	s_cmp_ge_i32 s11, s19
	s_mov_b64 s[0:1], -1
	s_cbranch_scc1 .LBB0_204
	s_lshl_b32 s4, s11, 1
	s_cmpk_lt_i32 s11, 0x4000
	s_cselect_b64 s[0:1], -1, 0
	s_ashr_i32 s5, s4, 31
	s_add_i32 s30, s4, 0xffff8000
	s_cmpk_gt_i32 s11, 0x3fff
	s_cselect_b64 s[8:9], -1, 0
	s_and_b64 s[6:7], s[8:9], exec
	s_cselect_b32 s7, 0, s5
	s_cselect_b32 s6, s30, s4
	s_cselect_b32 s23, s99, s79
	s_cselect_b32 s26, s98, s78
	s_lshl_b64 s[24:25], s[6:7], 11
	s_add_u32 s24, s26, s24
	s_addc_u32 s25, s23, s25
	global_load_dwordx4 v[116:119], v170, s[24:25]
	global_load_dwordx4 v[112:115], v170, s[24:25] offset:1024
	global_load_dwordx4 v[108:111], v170, s[24:25] offset:2048
	global_load_dwordx4 v[104:107], v170, s[24:25] offset:3072
	v_lshl_add_u64 v[248:249], s[24:25], 0, v[250:251]
	s_add_i32 s32, s11, s52
	s_cmpk_lt_i32 s32, 0x4000
	s_cselect_b32 s32, 1, 0
	s_and_b32 s32, s32, s82
	s_and_b64 vcc, exec, s[0:1]
	s_cbranch_vccnz .LBB0_213
	s_lshl_b64 s[24:25], s[30:31], 12
	v_lshl_add_u64 v[88:89], v[176:177], 0, s[24:25]
	v_add_co_u32_e32 v96, vcc, 0x800000, v88
	global_load_dwordx4 v[84:87], v[88:89], off offset:16
	global_load_dwordx4 v[80:83], v[88:89], off
	s_mov_b64 s[26:27], 0x800000
	v_addc_co_u32_e32 v97, vcc, 0, v89, vcc
	v_lshl_add_u64 v[94:95], v[88:89], 0, s[26:27]
	global_load_dwordx4 v[90:93], v[96:97], off
	global_load_dwordx4 v[126:129], v[94:95], off offset:16
	s_mov_b64 s[28:29], 0x1000000
	v_add_co_u32_e32 v122, vcc, 0x1000000, v88
	s_mov_b64 s[62:63], 0x1800000
	s_nop 0
	v_addc_co_u32_e32 v123, vcc, 0, v89, vcc
	v_add_co_u32_e32 v120, vcc, 0x1800000, v88
	v_lshl_add_u64 v[100:101], v[88:89], 0, s[62:63]
	s_nop 0
	v_addc_co_u32_e32 v121, vcc, 0, v89, vcc
	v_add_co_u32_e32 v102, vcc, 0x2000000, v88
	s_mov_b64 s[64:65], 0x2000000
	s_nop 0
	v_addc_co_u32_e32 v103, vcc, 0, v89, vcc
	v_add_co_u32_e32 v124, vcc, 0x2800000, v88
	s_mov_b64 s[68:69], 0x2800000
	s_nop 0
	v_addc_co_u32_e32 v125, vcc, 0, v89, vcc
	s_mov_b64 s[70:71], 0x3000000
	v_lshl_add_u64 v[142:143], v[88:89], 0, s[70:71]
	s_mov_b64 s[74:75], 0x3800000
	v_lshl_add_u64 v[146:147], v[88:89], 0, s[74:75]
	s_mov_b64 s[76:77], 0x800800
	s_mov_b64 s[40:41], s[34:35]
	s_mov_b64 s[34:35], 0x1000800
	s_mov_b64 s[86:87], 0x1800800
	s_mov_b64 s[94:95], 0x2000800
	s_mov_b64 s[14:15], 0x2800800
	s_mov_b32 s33, s96
	s_mov_b32 s39, s97
	s_mov_b64 s[96:97], 0x3000800
	s_mov_b64 s[36:37], 0x3800800
	s_add_i32 s30, s4, 0xffff8001
	s_lshl_b64 s[24:25], s[30:31], 12
	s_mov_b32 s23, 0x1000000
	s_waitcnt vmcnt(0)
	v_pk_add_f32 v[98:99], v[82:83], v[92:93]
	v_lshl_add_u64 v[92:93], v[88:89], 0, s[28:29]
	v_pk_add_f32 v[90:91], v[80:81], v[90:91]
	global_load_dwordx4 v[80:83], v[122:123], off
	s_nop 0
	global_load_dwordx4 v[92:95], v[92:93], off offset:16
	v_pk_add_f32 v[86:87], v[86:87], v[128:129]
	v_pk_add_f32 v[84:85], v[84:85], v[126:127]
	s_waitcnt vmcnt(1)
	v_pk_add_f32 v[98:99], v[98:99], v[82:83]
	v_pk_add_f32 v[90:91], v[90:91], v[80:81]
	global_load_dwordx4 v[80:83], v[120:121], off
	global_load_dwordx4 v[130:133], v[100:101], off offset:16
	v_lshl_add_u64 v[100:101], v[88:89], 0, s[64:65]
	s_waitcnt vmcnt(2)
	v_pk_add_f32 v[86:87], v[86:87], v[94:95]
	v_pk_add_f32 v[84:85], v[84:85], v[92:93]
	s_waitcnt vmcnt(1)
	v_pk_add_f32 v[98:99], v[98:99], v[82:83]
	v_pk_add_f32 v[90:91], v[90:91], v[80:81]
	global_load_dwordx4 v[80:83], v[102:103], off
	global_load_dwordx4 v[134:137], v[100:101], off offset:16
	v_lshl_add_u64 v[100:101], v[88:89], 0, s[68:69]
	s_waitcnt vmcnt(2)
	v_pk_add_f32 v[86:87], v[86:87], v[132:133]
	v_pk_add_f32 v[84:85], v[84:85], v[130:131]
	s_waitcnt vmcnt(1)
	v_pk_add_f32 v[98:99], v[98:99], v[82:83]
	v_pk_add_f32 v[90:91], v[90:91], v[80:81]
	global_load_dwordx4 v[80:83], v[124:125], off
	global_load_dwordx4 v[138:141], v[100:101], off offset:16
	v_add_co_u32_e32 v100, vcc, 0x3000000, v88
	s_waitcnt vmcnt(2)
	v_pk_add_f32 v[86:87], v[86:87], v[136:137]
	v_addc_co_u32_e32 v101, vcc, 0, v89, vcc
	v_pk_add_f32 v[84:85], v[84:85], v[134:135]
	s_waitcnt vmcnt(1)
	v_pk_add_f32 v[98:99], v[98:99], v[82:83]
	v_pk_add_f32 v[90:91], v[90:91], v[80:81]
	global_load_dwordx4 v[80:83], v[100:101], off
	s_nop 0
	global_load_dwordx4 v[142:145], v[142:143], off offset:16
	s_waitcnt vmcnt(2)
	v_pk_add_f32 v[84:85], v[84:85], v[138:139]
	v_pk_add_f32 v[86:87], v[86:87], v[140:141]
	s_waitcnt vmcnt(1)
	v_pk_add_f32 v[150:151], v[90:91], v[80:81]
	v_add_co_u32_e32 v90, vcc, 0x3800000, v88
	v_pk_add_f32 v[98:99], v[98:99], v[82:83]
	s_nop 0
	v_addc_co_u32_e32 v91, vcc, 0, v89, vcc
	global_load_dwordx4 v[80:83], v[90:91], off
	s_nop 0
	global_load_dwordx4 v[146:149], v[146:147], off offset:16
	s_nop 0
	global_load_dwordx4 v[92:95], v[88:89], off offset:2064
	global_load_dwordx4 v[126:129], v[88:89], off offset:2048
	s_waitcnt vmcnt(4)
	v_pk_add_f32 v[84:85], v[84:85], v[142:143]
	v_pk_add_f32 v[86:87], v[86:87], v[144:145]
	s_waitcnt vmcnt(3)
	v_pk_add_f32 v[82:83], v[98:99], v[82:83]
	v_lshl_add_u64 v[98:99], v[88:89], 0, s[76:77]
	global_load_dwordx4 v[130:133], v[96:97], off offset:2048
	s_nop 0
	global_load_dwordx4 v[96:99], v[98:99], off offset:16
	s_waitcnt vmcnt(4)
	v_pk_add_f32 v[86:87], v[86:87], v[148:149]
	v_pk_add_f32 v[84:85], v[84:85], v[146:147]
	v_pk_add_f32 v[80:81], v[150:151], v[80:81]
	s_waitcnt vmcnt(1)
	v_pk_add_f32 v[136:137], v[126:127], v[130:131]
	v_lshl_add_u64 v[130:131], v[88:89], 0, s[34:35]
	v_pk_add_f32 v[134:135], v[128:129], v[132:133]
	global_load_dwordx4 v[126:129], v[122:123], off offset:2048
	s_nop 0
	global_load_dwordx4 v[130:133], v[130:131], off offset:16
	s_waitcnt vmcnt(2)
	v_pk_add_f32 v[92:93], v[92:93], v[96:97]
	v_pk_add_f32 v[94:95], v[94:95], v[98:99]
	s_waitcnt vmcnt(1)
; __device__ __forceinline__ void phase_rows(const Params& p, const RowArgs& a, int G, int wave, int lane) {
;     ...
;                 const float* part = (const float*)p.out;
; #pragma unroll
;                 for (int u = 0; u < 2; ++u)
; #pragma unroll
;                     for (int j = 0; j < 4; ++j) { const float* pp = part + (size_t)(m0 + u - ML) * DM + 8 * lane + 512 * (j >> 1) + 4 * (j & 1); f32x4 s = *(const f32x4*)pp;
; #pragma unroll
;                         for (int k = 1; k < pg8::KSPLIT; ++k) s += *(const f32x4*)(pp + (size_t)k * MC * DM);
;                         y[u][j] = s; }
	v_pk_add_f32 v[136:137], v[136:137], v[126:127]
	v_lshl_add_u64 v[126:127], v[88:89], 0, s[86:87]
	v_pk_add_f32 v[134:135], v[134:135], v[128:129]
	global_load_dwordx4 v[120:123], v[120:121], off offset:2048
	s_nop 0
	global_load_dwordx4 v[126:129], v[126:127], off offset:16
	s_waitcnt vmcnt(2)
	v_pk_add_f32 v[92:93], v[92:93], v[130:131]
	v_pk_add_f32 v[94:95], v[94:95], v[132:133]
	s_waitcnt vmcnt(1)
	v_pk_add_f32 v[138:139], v[134:135], v[122:123]
	v_lshl_add_u64 v[134:135], v[88:89], 0, s[94:95]
	v_pk_add_f32 v[140:141], v[136:137], v[120:121]
	global_load_dwordx4 v[120:123], v[102:103], off offset:2048
	s_nop 0
	global_load_dwordx4 v[134:137], v[134:135], off offset:16
	s_waitcnt vmcnt(2)
	v_pk_add_f32 v[92:93], v[92:93], v[126:127]
	v_pk_add_f32 v[94:95], v[94:95], v[128:129]
	s_waitcnt vmcnt(1)
	v_pk_add_f32 v[102:103], v[138:139], v[122:123]
	v_lshl_add_u64 v[138:139], v[88:89], 0, s[14:15]
	v_pk_add_f32 v[142:143], v[140:141], v[120:121]
	global_load_dwordx4 v[120:123], v[124:125], off offset:2048
	s_nop 0
	global_load_dwordx4 v[138:141], v[138:139], off offset:16
	s_waitcnt vmcnt(2)
	v_pk_add_f32 v[92:93], v[92:93], v[134:135]
	v_pk_add_f32 v[94:95], v[94:95], v[136:137]
	s_waitcnt vmcnt(1)
	v_pk_add_f32 v[142:143], v[142:143], v[120:121]
	v_lshl_add_u64 v[120:121], v[88:89], 0, s[96:97]
	v_pk_add_f32 v[124:125], v[102:103], v[122:123]
	global_load_dwordx4 v[100:103], v[100:101], off offset:2048
	s_nop 0
	global_load_dwordx4 v[120:123], v[120:121], off offset:16
	s_waitcnt vmcnt(2)
	v_pk_add_f32 v[92:93], v[92:93], v[138:139]
	v_pk_add_f32 v[94:95], v[94:95], v[140:141]
	s_waitcnt vmcnt(1)
	v_pk_add_f32 v[142:143], v[142:143], v[100:101]
	v_lshl_add_u64 v[100:101], v[88:89], 0, s[36:37]
	v_pk_add_f32 v[124:125], v[124:125], v[102:103]
	global_load_dwordx4 v[88:91], v[90:91], off offset:2048
	s_nop 0
	global_load_dwordx4 v[100:103], v[100:101], off offset:16
	s_waitcnt vmcnt(2)
	v_pk_add_f32 v[92:93], v[92:93], v[120:121]
	v_lshl_add_u64 v[120:121], v[176:177], 0, s[24:25]
	v_pk_add_f32 v[94:95], v[94:95], v[122:123]
	v_add_co_u32_e32 v128, vcc, s55, v120
	v_lshl_add_u64 v[126:127], v[120:121], 0, s[26:27]
	s_nop 0
	v_addc_co_u32_e32 v129, vcc, 0, v121, vcc
	v_add_co_u32_e32 v132, vcc, s23, v120
	s_mov_b32 s23, 0x1800000
	s_nop 0
	v_addc_co_u32_e32 v133, vcc, 0, v121, vcc
	v_add_co_u32_e32 v136, vcc, s23, v120
	v_lshl_add_u64 v[134:135], v[120:121], 0, s[62:63]
	s_nop 0
	v_addc_co_u32_e32 v137, vcc, 0, v121, vcc
	s_brev_b32 s23, 64
	s_waitcnt vmcnt(1)
	v_pk_add_f32 v[90:91], v[124:125], v[90:91]
	s_waitcnt vmcnt(0)
	v_pk_add_f32 v[94:95], v[94:95], v[102:103]
	v_pk_add_f32 v[92:93], v[92:93], v[100:101]
	global_load_dwordx4 v[100:103], v[120:121], off offset:16
	global_load_dwordx4 v[96:99], v[120:121], off
	global_load_dwordx4 v[122:125], v[128:129], off
	global_load_dwordx4 v[138:141], v[126:127], off offset:16
	v_pk_add_f32 v[88:89], v[142:143], v[88:89]
	v_lshl_add_u64 v[142:143], v[120:121], 0, s[64:65]
	s_waitcnt vmcnt(1)
	v_pk_add_f32 v[130:131], v[98:99], v[124:125]
	v_lshl_add_u64 v[124:125], v[120:121], 0, s[28:29]
	v_pk_add_f32 v[122:123], v[96:97], v[122:123]
	global_load_dwordx4 v[96:99], v[132:133], off
	s_nop 0
	global_load_dwordx4 v[124:127], v[124:125], off offset:16
	s_waitcnt vmcnt(2)
	v_pk_add_f32 v[102:103], v[102:103], v[140:141]
	v_pk_add_f32 v[100:101], v[100:101], v[138:139]
	s_waitcnt vmcnt(1)
	v_pk_add_f32 v[130:131], v[130:131], v[98:99]
	v_pk_add_f32 v[122:123], v[122:123], v[96:97]
	global_load_dwordx4 v[96:99], v[136:137], off
	global_load_dwordx4 v[178:181], v[134:135], off offset:16
	s_waitcnt vmcnt(2)
	v_pk_add_f32 v[102:103], v[102:103], v[126:127]
	v_pk_add_f32 v[100:101], v[100:101], v[124:125]
	s_waitcnt vmcnt(1)
	v_pk_add_f32 v[134:135], v[122:123], v[96:97]
	v_add_co_u32_e32 v122, vcc, s23, v120
	v_pk_add_f32 v[130:131], v[130:131], v[98:99]
	s_nop 0
	v_addc_co_u32_e32 v123, vcc, 0, v121, vcc
	global_load_dwordx4 v[96:99], v[122:123], off
	global_load_dwordx4 v[182:185], v[142:143], off offset:16
	s_mov_b32 s23, 0x2800000
	v_add_co_u32_e32 v144, vcc, s23, v120
	v_lshl_add_u64 v[142:143], v[120:121], 0, s[68:69]
	s_nop 0
	v_addc_co_u32_e32 v145, vcc, 0, v121, vcc
	s_mov_b32 s23, 0x3000000
	v_add_co_u32_e32 v148, vcc, s23, v120
	s_mov_b32 s23, 0x3800000
	s_nop 0
	v_addc_co_u32_e32 v149, vcc, 0, v121, vcc
	v_add_co_u32_e32 v152, vcc, s23, v120
	s_waitcnt vmcnt(2)
	v_pk_add_f32 v[102:103], v[102:103], v[180:181]
	v_addc_co_u32_e32 v153, vcc, 0, v121, vcc
	v_pk_add_f32 v[100:101], v[100:101], v[178:179]
	s_waitcnt vmcnt(1)
; __device__ __forceinline__ void phase_rows(const Params& p, const RowArgs& a, int G, int wave, int lane) {
;     ...
;                 const float* part = (const float*)p.out;
; #pragma unroll
;                 for (int u = 0; u < 2; ++u)
; #pragma unroll
;                     for (int j = 0; j < 4; ++j) { const float* pp = part + (size_t)(m0 + u - ML) * DM + 8 * lane + 512 * (j >> 1) + 4 * (j & 1); f32x4 s = *(const f32x4*)pp;
; #pragma unroll
;                         for (int k = 1; k < pg8::KSPLIT; ++k) s += *(const f32x4*)(pp + (size_t)k * MC * DM);
;                         y[u][j] = s; }
	v_pk_add_f32 v[130:131], v[130:131], v[98:99]
	v_pk_add_f32 v[134:135], v[134:135], v[96:97]
	global_load_dwordx4 v[96:99], v[144:145], off
	global_load_dwordx4 v[186:189], v[142:143], off offset:16
	v_lshl_add_u64 v[142:143], v[120:121], 0, s[70:71]
	s_waitcnt vmcnt(2)
	v_pk_add_f32 v[100:101], v[100:101], v[182:183]
	v_pk_add_f32 v[102:103], v[102:103], v[184:185]
	s_waitcnt vmcnt(1)
	v_pk_add_f32 v[130:131], v[130:131], v[98:99]
	v_pk_add_f32 v[134:135], v[134:135], v[96:97]
	global_load_dwordx4 v[96:99], v[148:149], off
	global_load_dwordx4 v[190:193], v[142:143], off offset:16
	v_lshl_add_u64 v[142:143], v[120:121], 0, s[74:75]
	s_waitcnt vmcnt(2)
	v_pk_add_f32 v[102:103], v[102:103], v[188:189]
	v_pk_add_f32 v[100:101], v[100:101], v[186:187]
	s_waitcnt vmcnt(1)
	v_pk_add_f32 v[130:131], v[130:131], v[98:99]
	v_pk_add_f32 v[134:135], v[134:135], v[96:97]
	global_load_dwordx4 v[96:99], v[152:153], off
	global_load_dwordx4 v[194:197], v[142:143], off offset:16
	global_load_dwordx4 v[124:127], v[120:121], off offset:2064
	global_load_dwordx4 v[138:141], v[120:121], off offset:2048
	s_waitcnt vmcnt(4)
	v_pk_add_f32 v[102:103], v[102:103], v[192:193]
	v_pk_add_f32 v[100:101], v[100:101], v[190:191]
	s_waitcnt vmcnt(3)
	v_pk_add_f32 v[98:99], v[130:131], v[98:99]
	v_lshl_add_u64 v[130:131], v[120:121], 0, s[76:77]
	global_load_dwordx4 v[178:181], v[128:129], off offset:2048
	s_nop 0
	global_load_dwordx4 v[128:131], v[130:131], off offset:16
	v_pk_add_f32 v[96:97], v[134:135], v[96:97]
	v_lshl_add_u64 v[134:135], v[120:121], 0, s[34:35]
	s_waitcnt vmcnt(4)
	v_pk_add_f32 v[102:103], v[102:103], v[196:197]
	v_pk_add_f32 v[100:101], v[100:101], v[194:195]
	s_mov_b64 s[34:35], s[40:41]
	s_waitcnt vmcnt(1)
	v_pk_add_f32 v[142:143], v[140:141], v[180:181]
	v_pk_add_f32 v[146:147], v[138:139], v[178:179]
	global_load_dwordx4 v[138:141], v[132:133], off offset:2048
	s_nop 0
	global_load_dwordx4 v[132:135], v[134:135], off offset:16
	s_waitcnt vmcnt(2)
	v_pk_add_f32 v[126:127], v[126:127], v[130:131]
	v_pk_add_f32 v[124:125], v[124:125], v[128:129]
	s_waitcnt vmcnt(1)
	v_pk_add_f32 v[146:147], v[146:147], v[138:139]
	v_lshl_add_u64 v[138:139], v[120:121], 0, s[86:87]
	v_pk_add_f32 v[150:151], v[142:143], v[140:141]
	global_load_dwordx4 v[140:143], v[136:137], off offset:2048
	s_nop 0
	global_load_dwordx4 v[136:139], v[138:139], off offset:16
	s_waitcnt vmcnt(2)
	v_pk_add_f32 v[126:127], v[126:127], v[134:135]
	v_pk_add_f32 v[124:125], v[124:125], v[132:133]
	s_mov_b32 s87, s38
	v_readlane_b32 s86, v255, 11
	s_waitcnt vmcnt(1)
	v_pk_add_f32 v[146:147], v[146:147], v[140:141]
	v_lshl_add_u64 v[140:141], v[120:121], 0, s[94:95]
	v_pk_add_f32 v[150:151], v[150:151], v[142:143]
	global_load_dwordx4 v[178:181], v[122:123], off offset:2048
	s_nop 0
	global_load_dwordx4 v[140:143], v[140:141], off offset:16
	s_waitcnt vmcnt(2)
	v_pk_add_f32 v[126:127], v[126:127], v[138:139]
	v_pk_add_f32 v[124:125], v[124:125], v[136:137]
	v_readlane_b32 s94, v255, 27
	v_readlane_b32 s95, v255, 28
	s_waitcnt vmcnt(1)
	v_pk_add_f32 v[122:123], v[150:151], v[180:181]
	v_pk_add_f32 v[150:151], v[146:147], v[178:179]
	v_lshl_add_u64 v[146:147], v[120:121], 0, s[14:15]
	global_load_dwordx4 v[178:181], v[144:145], off offset:2048
	s_nop 0
	global_load_dwordx4 v[144:147], v[146:147], off offset:16
	s_waitcnt vmcnt(2)
	v_pk_add_f32 v[126:127], v[126:127], v[142:143]
	v_pk_add_f32 v[124:125], v[124:125], v[140:141]
	s_waitcnt vmcnt(1)
	v_pk_add_f32 v[154:155], v[150:151], v[178:179]
	v_lshl_add_u64 v[150:151], v[120:121], 0, s[96:97]
	v_pk_add_f32 v[122:123], v[122:123], v[180:181]
	global_load_dwordx4 v[180:183], v[148:149], off offset:2048
	s_nop 0
	global_load_dwordx4 v[148:151], v[150:151], off offset:16
	s_waitcnt vmcnt(2)
	v_pk_add_f32 v[126:127], v[126:127], v[146:147]
	v_pk_add_f32 v[124:125], v[124:125], v[144:145]
	s_mov_b32 s97, s39
	s_mov_b32 s96, s33
	s_waitcnt vmcnt(1)
	v_pk_add_f32 v[180:181], v[154:155], v[180:181]
	v_lshl_add_u64 v[154:155], v[120:121], 0, s[36:37]
	v_pk_add_f32 v[178:179], v[122:123], v[182:183]
	global_load_dwordx4 v[120:123], v[152:153], off offset:2048
	s_nop 0
	global_load_dwordx4 v[152:155], v[154:155], off offset:16
	s_waitcnt vmcnt(2)
	v_pk_add_f32 v[126:127], v[126:127], v[150:151]
	v_pk_add_f32 v[124:125], v[124:125], v[148:149]
	s_waitcnt vmcnt(1)
	v_pk_add_f32 v[122:123], v[178:179], v[122:123]
	v_pk_add_f32 v[120:121], v[180:181], v[120:121]
	s_waitcnt vmcnt(0)
	v_pk_add_f32 v[126:127], v[126:127], v[154:155]
	v_pk_add_f32 v[124:125], v[124:125], v[152:153]

; __device__ __forceinline__ f32x4 bfx4_lo(u32x4 w) { return (f32x4){bf_lo(w.x), bf_hi(w.x), bf_lo(w.y), bf_hi(w.y)}; }
; __device__ __forceinline__ f32x4 bfx4_hi(u32x4 w) { return (f32x4){bf_lo(w.z), bf_hi(w.z), bf_lo(w.w), bf_hi(w.w)}; }
; __device__ __forceinline__ void phase_rows(const Params& p, const RowArgs& a, int G, int wave, int lane) {
;     ...
;         if (a.xin_f32) {
; #pragma unroll
;             for (int u = 0; u < 2; ++u)
; #pragma unroll
;                 for (int j = 0; j < 4; ++j) v[u][j] = *(const f32x4*)((const float*)xrb + xoff + u * DM + 8 * lane + 512 * (j >> 1) + 4 * (j & 1));
;         } else {
; #pragma unroll
;             for (int u = 0; u < 2; ++u)
; #pragma unroll
;                 for (int jb = 0; jb < 2; ++jb) { const u32x4 xw = *(const u32x4*)((const bf16_t*)xrb + xoff + u * DM + 8 * lane + 512 * jb); v[u][2 * jb] = bfx4_lo(xw); v[u][2 * jb + 1] = bfx4_hi(xw); }
;         }
.LBB0_220:
	v_and_b32_e32 v145, 64, v221
	v_xor_b32_e32 v146, 16, v221
	v_add_u32_e32 v145, 64, v145
	s_cmp_lg_u32 s32, 0
	s_cbranch_scc0 .Lrt0_205
	global_load_dword v247, v[248:249], off
	s_waitcnt vmcnt(1)
	s_branch .Lrt1_205

; __device__ __forceinline__ f32x4 bfx4_lo(u32x4 w) { return (f32x4){bf_lo(w.x), bf_hi(w.x), bf_lo(w.y), bf_hi(w.y)}; }
; __device__ __forceinline__ f32x4 bfx4_hi(u32x4 w) { return (f32x4){bf_lo(w.z), bf_hi(w.z), bf_lo(w.w), bf_hi(w.w)}; }
; __device__ __forceinline__ void phase_rows(const Params& p, const RowArgs& a, int G, int wave, int lane) {
;     ...
;         } else {
; #pragma unroll
;             for (int u = 0; u < 2; ++u)
; #pragma unroll
;                 for (int jb = 0; jb < 2; ++jb) { const u32x4 xw = *(const u32x4*)((const bf16_t*)xrb + xoff + u * DM + 8 * lane + 512 * jb); v[u][2 * jb] = bfx4_lo(xw); v[u][2 * jb + 1] = bfx4_hi(xw); }
;         }
.Lrt1_205:
	v_lshlrev_b32_e32 v138, 16, v116
	v_and_b32_e32 v139, 0xffff0000, v116
	v_lshlrev_b32_e32 v142, 16, v117
	v_and_b32_e32 v143, 0xffff0000, v117
	v_lshlrev_b32_e32 v134, 16, v118
	v_and_b32_e32 v135, 0xffff0000, v118
	v_lshlrev_b32_e32 v140, 16, v119
	v_and_b32_e32 v141, 0xffff0000, v119
	v_lshlrev_b32_e32 v130, 16, v112
	v_and_b32_e32 v131, 0xffff0000, v112
	v_lshlrev_b32_e32 v132, 16, v113
	v_and_b32_e32 v133, 0xffff0000, v113
	v_lshlrev_b32_e32 v128, 16, v114
	v_and_b32_e32 v129, 0xffff0000, v114
	v_lshlrev_b32_e32 v136, 16, v115
	v_and_b32_e32 v137, 0xffff0000, v115
	v_lshlrev_b32_e32 v112, 16, v108
	v_and_b32_e32 v113, 0xffff0000, v108
	v_lshlrev_b32_e32 v114, 16, v109
	v_and_b32_e32 v115, 0xffff0000, v109
	v_lshlrev_b32_e32 v108, 16, v110
	v_and_b32_e32 v109, 0xffff0000, v110
	v_lshlrev_b32_e32 v116, 16, v111
	v_and_b32_e32 v117, 0xffff0000, v111
	v_lshlrev_b32_e32 v110, 16, v104
	v_and_b32_e32 v111, 0xffff0000, v104
	v_lshlrev_b32_e32 v118, 16, v105
	v_and_b32_e32 v119, 0xffff0000, v105
	v_lshlrev_b32_e32 v104, 16, v106
	v_and_b32_e32 v105, 0xffff0000, v106
	v_lshlrev_b32_e32 v106, 16, v107
	v_and_b32_e32 v107, 0xffff0000, v107
	s_andn2_b64 vcc, exec, s[8:9]
	v_cmp_lt_i32_e64 s[0:1], v146, v145
	s_cbranch_vccz .LBB0_202
	v_mov_b32_e32 v144, v147
	s_branch .LBB0_203

; __device__ __forceinline__ void phase_rows(const Params& p, const RowArgs& a, int G, int wave, int lane) {
;     bf16_t* XN = (bf16_t*)(p.ws + WS_XN);
;     const int gw = blockIdx.x * NWAVES + wave, NGW = G * NWAVES;
;     f32x4 gpo[4], gpr[4];
; #pragma unroll
;     for (int j = 0; j < 4; ++j) { const int c = 8 * lane + 512 * (j >> 1) + 4 * (j & 1);
;         gpo[j] = a.has_y ? *(const f32x4*)(a.gpost + c) : (f32x4){0.f, 0.f, 0.f, 0.f};
;         gpr[j] = a.write_xn ? *(const f32x4*)(a.gpre + c) : (f32x4){0.f, 0.f, 0.f, 0.f}; }
;     const int wpb = NGW / NB;
;     const bool bmaj = (NGW % NB == 0) && ((SEQ / 2) % wpb == 0);
;     const int ppw = bmaj ? (SEQ / 2) / wpb : 0;
;     const int nit = bmaj ? ppw + ((a.nrows > ML) ? ((a.nrows - ML) / 2 + NGW - 1) / NGW : 0) : (a.nrows / 2 + NGW - 1) / NGW;
;     int cur_rb = -1;
;     f32x4 gt[4], sh[4], sc[4];
; #pragma unroll 1
;     for (int it = (a.ctx_only && bmaj) ? ppw : 0; it < nit; ++it) {
;         int mp;
;         if (bmaj) mp = (it < ppw) ? (gw / wpb) * (SEQ / 2) + (gw % wpb) + it * wpb : ML / 2 + gw + (it - ppw) * NGW;
;         else mp = ((a.ctx_only && !bmaj) ? ML / 2 : 0) + gw + it * NGW;
.LBB0_318:
	s_mul_hi_i32 s1, s0, 0x36000
	s_mul_i32 s0, s0, 0x36000
	s_add_u32 s13, s73, s0
	v_readlane_b32 s0, v254, 22
	s_addc_u32 s14, s57, s1
	s_add_i32 s15, s87, s0
	v_readlane_b32 s0, v255, 17
	v_readlane_b32 s1, v255, 18
	s_mov_b32 s4, s0
	s_mul_i32 s1, s4, 0x36000
	s_mul_hi_i32 s0, s0, 0x36000
	s_add_u32 s33, s73, s1
	s_addc_u32 s53, s57, s0
	s_abs_i32 s1, s15
	v_readlane_b32 s4, v254, 8
	s_mul_hi_u32 s4, s1, s4
	v_readlane_b32 s7, v254, 9
	s_mul_i32 s5, s4, s7
	s_ashr_i32 s0, s15, 31
	s_sub_i32 s1, s1, s5
	s_xor_b32 s0, s0, s59
	s_add_i32 s5, s4, 1
	s_sub_i32 s6, s1, s7
	s_cmp_ge_u32 s1, s7
	s_cselect_b32 s4, s5, s4
	s_cselect_b32 s1, s6, s1
	s_add_i32 s5, s4, 1
	s_cmp_ge_u32 s1, s7
	s_cselect_b32 s1, s5, s4
	s_xor_b32 s1, s1, s0
	s_sub_i32 s0, s1, s0
	v_lshlrev_b32_e32 v33, 3, v168
	s_lshl_b32 s1, s0, 11
	s_mul_i32 s0, s0, s3
	v_or_b32_e32 v32, 0x200, v33
	v_lshlrev_b32_e32 v170, 1, v33
	v_mov_b32_e32 v171, v157
	v_lshlrev_b32_e32 v156, 2, v33
	s_sub_i32 s18, s15, s0
	v_readlane_b32 s0, v254, 27
	v_mov_b32_e32 v48, 0
	v_lshl_add_u64 v[172:173], s[98:99], 0, v[170:171]
	v_lshl_add_u64 v[174:175], s[94:95], 0, v[170:171]
	v_lshl_add_u64 v[176:177], s[42:43], 0, v[156:157]
	s_add_i32 s18, s18, s1
	s_add_i32 s19, s0, s87
	s_mov_b32 s20, 0
	s_mov_b32 s10, -1
	v_lshlrev_b32_e32 v167, 2, v32
	v_and_b32_e32 v250, 0x1f0, v170
	v_lshlrev_b32_e32 v250, 3, v250
	s_lshl_b32 s32, s52, 12
	v_add_u32_e32 v250, s32, v250
	v_mov_b32_e32 v251, 0
	v_mov_b32_e32 v49, v48
	v_mov_b32_e32 v50, v48
	v_mov_b32_e32 v51, v48
	v_mov_b32_e32 v52, v48
	v_mov_b32_e32 v53, v48
	v_mov_b32_e32 v54, v48
	v_mov_b32_e32 v55, v48
	v_mov_b32_e32 v68, v48
	v_mov_b32_e32 v69, v48
	v_mov_b32_e32 v70, v48
	v_mov_b32_e32 v71, v48
	v_mov_b32_e32 v64, v48
	v_mov_b32_e32 v65, v48
	v_mov_b32_e32 v66, v48
	v_mov_b32_e32 v67, v48
	v_mov_b32_e32 v60, v48
	v_mov_b32_e32 v61, v48
	v_mov_b32_e32 v62, v48
	v_mov_b32_e32 v63, v48
	v_mov_b32_e32 v56, v48
	v_mov_b32_e32 v57, v48
	v_mov_b32_e32 v58, v48
	v_mov_b32_e32 v59, v48
	v_mov_b32_e32 v76, v48
	v_mov_b32_e32 v77, v48
	v_mov_b32_e32 v78, v48
	v_mov_b32_e32 v79, v48
	v_mov_b32_e32 v72, v48
	v_mov_b32_e32 v73, v48
	v_mov_b32_e32 v74, v48
	v_mov_b32_e32 v75, v48
	s_branch .LBB0_322

; __device__ __forceinline__ f32x4 bfx4_lo(u32x4 w) { return (f32x4){bf_lo(w.x), bf_hi(w.x), bf_lo(w.y), bf_hi(w.y)}; }
; __device__ __forceinline__ void phase_rows(const Params& p, const RowArgs& a, int G, int wave, int lane) {
;     ...
;         if (bmaj) mp = (it < ppw) ? (gw / wpb) * (SEQ / 2) + (gw % wpb) + it * wpb : ML / 2 + gw + (it - ppw) * NGW;
;         else mp = ((a.ctx_only && !bmaj) ? ML / 2 : 0) + gw + it * NGW;
;         if (mp >= a.nrows / 2) break;
;         const int m0 = 2 * mp; const bool isl = m0 < ML; const int rb = isl ? (m0 >> 12) : 8;
;         const bool use_y = a.has_y && !(a.lat_no_y && isl);
;         const size_t xoff = isl ? (size_t)m0 * DM : (size_t)(m0 - ML) * DM;
;         const void* xrb = isl ? a.xlat : a.xctx; void* xob = isl ? a.olat : a.octx;
;         bf16_t* xn = XN + (size_t)m0 * DM;
;         const size_t moff = (size_t)rb * NMOD;
;         f32x4 v[2][4], y[2][4];
;         if (a.xin_f32) {
; #pragma unroll
;             for (int u = 0; u < 2; ++u)
; #pragma unroll
;                 for (int j = 0; j < 4; ++j) v[u][j] = *(const f32x4*)((const float*)xrb + xoff + u * DM + 8 * lane + 512 * (j >> 1) + 4 * (j & 1));
;         } else {
; #pragma unroll
;             for (int u = 0; u < 2; ++u)
; #pragma unroll
;                 for (int jb = 0; jb < 2; ++jb) { const u32x4 xw = *(const u32x4*)((const bf16_t*)xrb + xoff + u * DM + 8 * lane + 512 * jb); v[u][2 * jb] = bfx4_lo(xw); v[u][2 * jb + 1] = bfx4_hi(xw); }
;         }
;         if (use_y) {
;             if (isl || !a.ctx_split) {
; #pragma unroll
;                 for (int u = 0; u < 2; ++u)
; #pragma unroll
;                     for (int jb = 0; jb < 2; ++jb) { const u32x4 yw = *(const u32x4*)(xn + u * DM + 8 * lane + 512 * jb); y[u][2 * jb] = bfx4_lo(yw); y[u][2 * jb + 1] = bfx4_hi(yw); }
;             } else {
;                 const float* part = (const float*)p.out;
; #pragma unroll
;                 for (int u = 0; u < 2; ++u)
; #pragma unroll
;                     for (int j = 0; j < 4; ++j) { const float* pp = part + (size_t)(m0 + u - ML) * DM + 8 * lane + 512 * (j >> 1) + 4 * (j & 1); f32x4 s = *(const f32x4*)pp;
; #pragma unroll
;                         for (int k = 1; k < pg8::KSPLIT; ++k) s += *(const f32x4*)(pp + (size_t)k * MC * DM);
;                         y[u][j] = s; }
.LBB0_327:
	s_cmpk_gt_i32 s11, 0x43ff
	s_mov_b64 s[0:1], -1
	s_cbranch_scc1 .LBB0_321
	s_lshl_b32 s4, s11, 1
	s_cmpk_lt_i32 s11, 0x4000
	s_cselect_b64 s[0:1], -1, 0
	s_ashr_i32 s5, s4, 31
	s_add_i32 s30, s4, 0xffff8000
	s_cmpk_gt_i32 s11, 0x3fff
	s_cselect_b64 s[8:9], -1, 0
	s_and_b64 s[6:7], s[8:9], exec
	s_cselect_b32 s7, 0, s5
	s_cselect_b32 s6, s30, s4
	s_cselect_b32 s21, s99, s79
	s_cselect_b32 s24, s98, s78
	s_lshl_b64 s[22:23], s[6:7], 11
	s_add_u32 s22, s24, s22
	s_addc_u32 s23, s21, s23
	global_load_dwordx4 v[116:119], v170, s[22:23]
	global_load_dwordx4 v[112:115], v170, s[22:23] offset:1024
	global_load_dwordx4 v[108:111], v170, s[22:23] offset:2048
	global_load_dwordx4 v[104:107], v170, s[22:23] offset:3072
	v_lshl_add_u64 v[248:249], s[22:23], 0, v[250:251]
	s_add_i32 s32, s11, s52
	s_cmpk_lt_i32 s32, 0x4000
	s_cselect_b32 s32, 1, 0
	v_readlane_b32 vcc_lo, v254, 17
	s_nop 0
	s_and_b32 s32, s32, vcc_lo
	s_and_b64 vcc, exec, s[0:1]
	s_cbranch_vccnz .LBB0_330
	s_lshl_b64 s[22:23], s[30:31], 12
	v_lshl_add_u64 v[88:89], v[176:177], 0, s[22:23]
	v_add_co_u32_e32 v96, vcc, 0x800000, v88
	global_load_dwordx4 v[84:87], v[88:89], off offset:16
	global_load_dwordx4 v[80:83], v[88:89], off
	s_mov_b64 s[24:25], 0x800000
	v_addc_co_u32_e32 v97, vcc, 0, v89, vcc
	v_lshl_add_u64 v[94:95], v[88:89], 0, s[24:25]
	global_load_dwordx4 v[90:93], v[96:97], off
	global_load_dwordx4 v[126:129], v[94:95], off offset:16
	s_mov_b64 s[26:27], 0x1000000
	v_add_co_u32_e32 v120, vcc, 0x1000000, v88
	s_mov_b64 s[28:29], 0x1800000
	s_nop 0
	v_addc_co_u32_e32 v121, vcc, 0, v89, vcc
	v_add_co_u32_e32 v122, vcc, 0x1800000, v88
	v_lshl_add_u64 v[100:101], v[88:89], 0, s[28:29]
	s_nop 0
	v_addc_co_u32_e32 v123, vcc, 0, v89, vcc
	v_add_co_u32_e32 v102, vcc, 0x2000000, v88
	s_mov_b64 s[34:35], 0x2000000
	s_nop 0
	v_addc_co_u32_e32 v103, vcc, 0, v89, vcc
	v_add_co_u32_e32 v124, vcc, 0x2800000, v88
	s_mov_b64 s[62:63], 0x2800000
	s_nop 0
	v_addc_co_u32_e32 v125, vcc, 0, v89, vcc
	s_mov_b64 s[64:65], 0x3000000
	v_lshl_add_u64 v[142:143], v[88:89], 0, s[64:65]
	s_mov_b64 s[68:69], 0x3800000
	v_lshl_add_u64 v[146:147], v[88:89], 0, s[68:69]
	s_mov_b64 s[70:71], 0x800800
	s_mov_b64 s[74:75], 0x1000800
	s_mov_b64 s[76:77], 0x1800800
	s_mov_b64 s[94:95], 0x2000800
	s_mov_b64 s[16:17], 0x2800800
	s_mov_b32 s38, s96
	s_mov_b64 s[96:97], 0x3000800
	s_mov_b64 s[36:37], 0x3800800
	s_add_i32 s30, s4, 0xffff8001
	s_lshl_b64 s[22:23], s[30:31], 12
	s_mov_b32 s21, 0x1000000
	s_waitcnt vmcnt(1)
	v_pk_add_f32 v[98:99], v[82:83], v[92:93]
	v_lshl_add_u64 v[92:93], v[88:89], 0, s[26:27]
	v_pk_add_f32 v[90:91], v[80:81], v[90:91]
	global_load_dwordx4 v[80:83], v[120:121], off
	s_nop 0
	global_load_dwordx4 v[92:95], v[92:93], off offset:16
	s_waitcnt vmcnt(2)
	v_pk_add_f32 v[86:87], v[86:87], v[128:129]
	v_pk_add_f32 v[84:85], v[84:85], v[126:127]
	s_waitcnt vmcnt(1)
	v_pk_add_f32 v[98:99], v[98:99], v[82:83]
	v_pk_add_f32 v[90:91], v[90:91], v[80:81]
	global_load_dwordx4 v[80:83], v[122:123], off
	global_load_dwordx4 v[130:133], v[100:101], off offset:16
	v_lshl_add_u64 v[100:101], v[88:89], 0, s[34:35]
	s_waitcnt vmcnt(2)
	v_pk_add_f32 v[86:87], v[86:87], v[94:95]
	v_pk_add_f32 v[84:85], v[84:85], v[92:93]
	s_waitcnt vmcnt(1)
	v_pk_add_f32 v[98:99], v[98:99], v[82:83]
	v_pk_add_f32 v[90:91], v[90:91], v[80:81]
	global_load_dwordx4 v[80:83], v[102:103], off
	global_load_dwordx4 v[134:137], v[100:101], off offset:16
	v_lshl_add_u64 v[100:101], v[88:89], 0, s[62:63]
	s_waitcnt vmcnt(2)
	v_pk_add_f32 v[86:87], v[86:87], v[132:133]
	v_pk_add_f32 v[84:85], v[84:85], v[130:131]
	s_waitcnt vmcnt(1)
	v_pk_add_f32 v[98:99], v[98:99], v[82:83]
	v_pk_add_f32 v[90:91], v[90:91], v[80:81]
	global_load_dwordx4 v[80:83], v[124:125], off
	global_load_dwordx4 v[138:141], v[100:101], off offset:16
	v_add_co_u32_e32 v100, vcc, 0x3000000, v88
	s_waitcnt vmcnt(2)
	v_pk_add_f32 v[86:87], v[86:87], v[136:137]
	v_addc_co_u32_e32 v101, vcc, 0, v89, vcc
	v_pk_add_f32 v[84:85], v[84:85], v[134:135]
	s_waitcnt vmcnt(1)
	v_pk_add_f32 v[98:99], v[98:99], v[82:83]
	v_pk_add_f32 v[90:91], v[90:91], v[80:81]
	global_load_dwordx4 v[80:83], v[100:101], off
	s_nop 0
	global_load_dwordx4 v[142:145], v[142:143], off offset:16
	s_waitcnt vmcnt(2)
	v_pk_add_f32 v[84:85], v[84:85], v[138:139]
	v_pk_add_f32 v[86:87], v[86:87], v[140:141]
	s_waitcnt vmcnt(1)
	v_pk_add_f32 v[150:151], v[90:91], v[80:81]
	v_add_co_u32_e32 v90, vcc, 0x3800000, v88
	v_pk_add_f32 v[98:99], v[98:99], v[82:83]
	s_nop 0
	v_addc_co_u32_e32 v91, vcc, 0, v89, vcc
	global_load_dwordx4 v[80:83], v[90:91], off
	s_nop 0
	global_load_dwordx4 v[146:149], v[146:147], off offset:16
	s_nop 0
	global_load_dwordx4 v[92:95], v[88:89], off offset:2064
	global_load_dwordx4 v[126:129], v[88:89], off offset:2048
	s_waitcnt vmcnt(4)
	v_pk_add_f32 v[84:85], v[84:85], v[142:143]
	v_pk_add_f32 v[86:87], v[86:87], v[144:145]
	s_waitcnt vmcnt(3)
	v_pk_add_f32 v[82:83], v[98:99], v[82:83]
	v_lshl_add_u64 v[98:99], v[88:89], 0, s[70:71]
	global_load_dwordx4 v[130:133], v[96:97], off offset:2048
	s_nop 0
	global_load_dwordx4 v[96:99], v[98:99], off offset:16
	s_waitcnt vmcnt(4)
	v_pk_add_f32 v[86:87], v[86:87], v[148:149]
	v_pk_add_f32 v[84:85], v[84:85], v[146:147]
	v_pk_add_f32 v[80:81], v[150:151], v[80:81]
	s_waitcnt vmcnt(1)
	v_pk_add_f32 v[136:137], v[126:127], v[130:131]
	v_lshl_add_u64 v[130:131], v[88:89], 0, s[74:75]
	v_pk_add_f32 v[134:135], v[128:129], v[132:133]
	global_load_dwordx4 v[126:129], v[120:121], off offset:2048
	s_nop 0
	global_load_dwordx4 v[130:133], v[130:131], off offset:16
	s_waitcnt vmcnt(2)
	v_pk_add_f32 v[92:93], v[92:93], v[96:97]
	v_pk_add_f32 v[94:95], v[94:95], v[98:99]
	s_waitcnt vmcnt(1)
; __device__ __forceinline__ void phase_rows(const Params& p, const RowArgs& a, int G, int wave, int lane) {
;     ...
;                 const float* part = (const float*)p.out;
; #pragma unroll
;                 for (int u = 0; u < 2; ++u)
; #pragma unroll
;                     for (int j = 0; j < 4; ++j) { const float* pp = part + (size_t)(m0 + u - ML) * DM + 8 * lane + 512 * (j >> 1) + 4 * (j & 1); f32x4 s = *(const f32x4*)pp;
; #pragma unroll
;                         for (int k = 1; k < pg8::KSPLIT; ++k) s += *(const f32x4*)(pp + (size_t)k * MC * DM);
;                         y[u][j] = s; }
	v_pk_add_f32 v[136:137], v[136:137], v[126:127]
	v_lshl_add_u64 v[126:127], v[88:89], 0, s[76:77]
	v_pk_add_f32 v[134:135], v[134:135], v[128:129]
	global_load_dwordx4 v[120:123], v[122:123], off offset:2048
	s_nop 0
	global_load_dwordx4 v[126:129], v[126:127], off offset:16
	s_waitcnt vmcnt(2)
	v_pk_add_f32 v[92:93], v[92:93], v[130:131]
	v_pk_add_f32 v[94:95], v[94:95], v[132:133]
	s_waitcnt vmcnt(1)
	v_pk_add_f32 v[138:139], v[134:135], v[122:123]
	v_lshl_add_u64 v[134:135], v[88:89], 0, s[94:95]
	v_pk_add_f32 v[140:141], v[136:137], v[120:121]
	global_load_dwordx4 v[120:123], v[102:103], off offset:2048
	s_nop 0
	global_load_dwordx4 v[134:137], v[134:135], off offset:16
	s_waitcnt vmcnt(2)
	v_pk_add_f32 v[92:93], v[92:93], v[126:127]
	v_pk_add_f32 v[94:95], v[94:95], v[128:129]
	s_waitcnt vmcnt(1)
	v_pk_add_f32 v[102:103], v[138:139], v[122:123]
	v_lshl_add_u64 v[138:139], v[88:89], 0, s[16:17]
	v_pk_add_f32 v[142:143], v[140:141], v[120:121]
	global_load_dwordx4 v[120:123], v[124:125], off offset:2048
	s_nop 0
	global_load_dwordx4 v[138:141], v[138:139], off offset:16
	s_waitcnt vmcnt(2)
	v_pk_add_f32 v[92:93], v[92:93], v[134:135]
	v_pk_add_f32 v[94:95], v[94:95], v[136:137]
	s_waitcnt vmcnt(1)
	v_pk_add_f32 v[142:143], v[142:143], v[120:121]
	v_lshl_add_u64 v[120:121], v[88:89], 0, s[96:97]
	v_pk_add_f32 v[124:125], v[102:103], v[122:123]
	global_load_dwordx4 v[100:103], v[100:101], off offset:2048
	s_nop 0
	global_load_dwordx4 v[120:123], v[120:121], off offset:16
	s_waitcnt vmcnt(2)
	v_pk_add_f32 v[92:93], v[92:93], v[138:139]
	v_pk_add_f32 v[94:95], v[94:95], v[140:141]
	s_waitcnt vmcnt(1)
	v_pk_add_f32 v[142:143], v[142:143], v[100:101]
	v_lshl_add_u64 v[100:101], v[88:89], 0, s[36:37]
	v_pk_add_f32 v[124:125], v[124:125], v[102:103]
	global_load_dwordx4 v[88:91], v[90:91], off offset:2048
	s_nop 0
	global_load_dwordx4 v[100:103], v[100:101], off offset:16
	s_waitcnt vmcnt(2)
	v_pk_add_f32 v[92:93], v[92:93], v[120:121]
	v_lshl_add_u64 v[120:121], v[176:177], 0, s[22:23]
	v_pk_add_f32 v[94:95], v[94:95], v[122:123]
	v_add_co_u32_e32 v122, vcc, s55, v120
	v_lshl_add_u64 v[128:129], v[120:121], 0, s[24:25]
	s_nop 0
	v_addc_co_u32_e32 v123, vcc, 0, v121, vcc
	v_add_co_u32_e32 v132, vcc, s21, v120
	s_mov_b32 s21, 0x1800000
	s_nop 0
	v_addc_co_u32_e32 v133, vcc, 0, v121, vcc
	v_lshl_add_u64 v[140:141], v[120:121], 0, s[28:29]
	s_waitcnt vmcnt(1)
	v_pk_add_f32 v[90:91], v[124:125], v[90:91]
	s_waitcnt vmcnt(0)
	v_pk_add_f32 v[94:95], v[94:95], v[102:103]
	v_pk_add_f32 v[92:93], v[92:93], v[100:101]
	global_load_dwordx4 v[100:103], v[120:121], off offset:16
	global_load_dwordx4 v[96:99], v[120:121], off
	global_load_dwordx4 v[124:127], v[122:123], off
	s_nop 0
	global_load_dwordx4 v[128:131], v[128:129], off offset:16
	v_pk_add_f32 v[88:89], v[142:143], v[88:89]
	v_lshl_add_u64 v[142:143], v[120:121], 0, s[34:35]
	s_waitcnt vmcnt(1)
	v_pk_add_f32 v[136:137], v[96:97], v[124:125]
	v_lshl_add_u64 v[124:125], v[120:121], 0, s[26:27]
	v_pk_add_f32 v[134:135], v[98:99], v[126:127]
	global_load_dwordx4 v[96:99], v[132:133], off
	s_nop 0
	global_load_dwordx4 v[124:127], v[124:125], off offset:16
	s_waitcnt vmcnt(2)
	v_pk_add_f32 v[102:103], v[102:103], v[130:131]
	v_pk_add_f32 v[100:101], v[100:101], v[128:129]
	v_lshl_add_u64 v[128:129], v[120:121], 0, s[70:71]
	s_waitcnt vmcnt(1)
	v_pk_add_f32 v[138:139], v[136:137], v[96:97]
	v_add_co_u32_e32 v136, vcc, s21, v120
	v_pk_add_f32 v[134:135], v[134:135], v[98:99]
	s_nop 0
	v_addc_co_u32_e32 v137, vcc, 0, v121, vcc
	global_load_dwordx4 v[96:99], v[136:137], off
	global_load_dwordx4 v[178:181], v[140:141], off offset:16
	s_brev_b32 s21, 64
	v_add_co_u32_e32 v140, vcc, s21, v120
	s_mov_b32 s21, 0x2800000
	s_nop 0
	v_addc_co_u32_e32 v141, vcc, 0, v121, vcc
	v_add_co_u32_e32 v144, vcc, s21, v120
	s_mov_b32 s21, 0x3000000
	s_nop 0
	v_addc_co_u32_e32 v145, vcc, 0, v121, vcc
	v_add_co_u32_e32 v148, vcc, s21, v120
	s_mov_b32 s21, 0x3800000
	s_nop 0
	v_addc_co_u32_e32 v149, vcc, 0, v121, vcc
	v_add_co_u32_e32 v152, vcc, s21, v120
	s_waitcnt vmcnt(2)
	v_pk_add_f32 v[102:103], v[102:103], v[126:127]
	v_addc_co_u32_e32 v153, vcc, 0, v121, vcc
	v_pk_add_f32 v[100:101], v[100:101], v[124:125]
	s_waitcnt vmcnt(1)
	v_pk_add_f32 v[134:135], v[134:135], v[98:99]
	v_pk_add_f32 v[138:139], v[138:139], v[96:97]
	global_load_dwordx4 v[96:99], v[140:141], off
	global_load_dwordx4 v[182:185], v[142:143], off offset:16
	v_lshl_add_u64 v[142:143], v[120:121], 0, s[62:63]
	s_waitcnt vmcnt(2)
; __device__ __forceinline__ void phase_rows(const Params& p, const RowArgs& a, int G, int wave, int lane) {
;     ...
;                 const float* part = (const float*)p.out;
; #pragma unroll
;                 for (int u = 0; u < 2; ++u)
; #pragma unroll
;                     for (int j = 0; j < 4; ++j) { const float* pp = part + (size_t)(m0 + u - ML) * DM + 8 * lane + 512 * (j >> 1) + 4 * (j & 1); f32x4 s = *(const f32x4*)pp;
; #pragma unroll
;                         for (int k = 1; k < pg8::KSPLIT; ++k) s += *(const f32x4*)(pp + (size_t)k * MC * DM);
;                         y[u][j] = s; }
	v_pk_add_f32 v[102:103], v[102:103], v[180:181]
	v_pk_add_f32 v[100:101], v[100:101], v[178:179]
	s_waitcnt vmcnt(1)
	v_pk_add_f32 v[134:135], v[134:135], v[98:99]
	v_pk_add_f32 v[138:139], v[138:139], v[96:97]
	global_load_dwordx4 v[96:99], v[144:145], off
	global_load_dwordx4 v[186:189], v[142:143], off offset:16
	v_lshl_add_u64 v[142:143], v[120:121], 0, s[64:65]
	s_waitcnt vmcnt(2)
	v_pk_add_f32 v[102:103], v[102:103], v[184:185]
	v_pk_add_f32 v[100:101], v[100:101], v[182:183]
	s_waitcnt vmcnt(1)
	v_pk_add_f32 v[134:135], v[134:135], v[98:99]
	v_pk_add_f32 v[138:139], v[138:139], v[96:97]
	global_load_dwordx4 v[96:99], v[148:149], off
	global_load_dwordx4 v[190:193], v[142:143], off offset:16
	v_lshl_add_u64 v[142:143], v[120:121], 0, s[68:69]
	s_waitcnt vmcnt(2)
	v_pk_add_f32 v[102:103], v[102:103], v[188:189]
	v_pk_add_f32 v[100:101], v[100:101], v[186:187]
	s_waitcnt vmcnt(1)
	v_pk_add_f32 v[134:135], v[134:135], v[98:99]
	v_pk_add_f32 v[138:139], v[138:139], v[96:97]
	global_load_dwordx4 v[96:99], v[152:153], off
	global_load_dwordx4 v[194:197], v[142:143], off offset:16
	global_load_dwordx4 v[124:127], v[120:121], off offset:2064
	global_load_dwordx4 v[178:181], v[120:121], off offset:2048
	global_load_dwordx4 v[182:185], v[122:123], off offset:2048
	s_nop 0
	global_load_dwordx4 v[128:131], v[128:129], off offset:16
	s_waitcnt vmcnt(6)
	v_pk_add_f32 v[102:103], v[102:103], v[192:193]
	v_pk_add_f32 v[100:101], v[100:101], v[190:191]
	s_waitcnt vmcnt(5)
	v_pk_add_f32 v[98:99], v[134:135], v[98:99]
	v_lshl_add_u64 v[134:135], v[120:121], 0, s[74:75]
	v_pk_add_f32 v[96:97], v[138:139], v[96:97]
	s_waitcnt vmcnt(1)
	v_pk_add_f32 v[122:123], v[180:181], v[184:185]
	v_pk_add_f32 v[138:139], v[178:179], v[182:183]
	global_load_dwordx4 v[178:181], v[132:133], off offset:2048
	s_nop 0
	global_load_dwordx4 v[132:135], v[134:135], off offset:16
	s_waitcnt vmcnt(2)
	v_pk_add_f32 v[126:127], v[126:127], v[130:131]
	v_pk_add_f32 v[124:125], v[124:125], v[128:129]
	v_pk_add_f32 v[102:103], v[102:103], v[196:197]
	v_pk_add_f32 v[100:101], v[100:101], v[194:195]
	s_waitcnt vmcnt(1)
	v_pk_add_f32 v[142:143], v[138:139], v[178:179]
	v_lshl_add_u64 v[138:139], v[120:121], 0, s[76:77]
	v_pk_add_f32 v[122:123], v[122:123], v[180:181]
	global_load_dwordx4 v[178:181], v[136:137], off offset:2048
	s_nop 0
	global_load_dwordx4 v[136:139], v[138:139], off offset:16
	s_waitcnt vmcnt(2)
	v_pk_add_f32 v[126:127], v[126:127], v[134:135]
	v_pk_add_f32 v[124:125], v[124:125], v[132:133]
	s_waitcnt vmcnt(1)
	v_pk_add_f32 v[146:147], v[142:143], v[178:179]
	v_lshl_add_u64 v[142:143], v[120:121], 0, s[94:95]
	v_pk_add_f32 v[122:123], v[122:123], v[180:181]
	global_load_dwordx4 v[178:181], v[140:141], off offset:2048
	s_nop 0
	global_load_dwordx4 v[140:143], v[142:143], off offset:16
	s_waitcnt vmcnt(2)
	v_pk_add_f32 v[126:127], v[126:127], v[138:139]
	v_pk_add_f32 v[124:125], v[124:125], v[136:137]
	v_readlane_b32 s94, v255, 27
	v_readlane_b32 s95, v255, 28
	s_waitcnt vmcnt(1)
	v_pk_add_f32 v[150:151], v[146:147], v[178:179]
	v_lshl_add_u64 v[146:147], v[120:121], 0, s[16:17]
	v_pk_add_f32 v[122:123], v[122:123], v[180:181]
	global_load_dwordx4 v[178:181], v[144:145], off offset:2048
	s_nop 0
	global_load_dwordx4 v[144:147], v[146:147], off offset:16
	s_waitcnt vmcnt(2)
	v_pk_add_f32 v[126:127], v[126:127], v[142:143]
	v_pk_add_f32 v[124:125], v[124:125], v[140:141]
	s_waitcnt vmcnt(1)
	v_pk_add_f32 v[154:155], v[150:151], v[178:179]
	v_lshl_add_u64 v[150:151], v[120:121], 0, s[96:97]
	v_pk_add_f32 v[122:123], v[122:123], v[180:181]
	global_load_dwordx4 v[180:183], v[148:149], off offset:2048
	s_nop 0
	global_load_dwordx4 v[148:151], v[150:151], off offset:16
	s_waitcnt vmcnt(2)
	v_pk_add_f32 v[126:127], v[126:127], v[146:147]
	v_pk_add_f32 v[124:125], v[124:125], v[144:145]
	s_mov_b32 s96, s38
	s_waitcnt vmcnt(1)
	v_pk_add_f32 v[180:181], v[154:155], v[180:181]
	v_lshl_add_u64 v[154:155], v[120:121], 0, s[36:37]
	v_pk_add_f32 v[178:179], v[122:123], v[182:183]
	global_load_dwordx4 v[120:123], v[152:153], off offset:2048
	s_nop 0
	global_load_dwordx4 v[152:155], v[154:155], off offset:16
	s_waitcnt vmcnt(2)
	v_pk_add_f32 v[126:127], v[126:127], v[150:151]
	v_pk_add_f32 v[124:125], v[124:125], v[148:149]
	s_waitcnt vmcnt(1)
	v_pk_add_f32 v[122:123], v[178:179], v[122:123]
	v_pk_add_f32 v[120:121], v[180:181], v[120:121]
	s_waitcnt vmcnt(0)
	v_pk_add_f32 v[126:127], v[126:127], v[154:155]
	v_pk_add_f32 v[124:125], v[124:125], v[152:153]
